# rwkv prep output stage: fragment copies and 32 ds_read_u16 batched (2 LDS round trips instead of 21), on top of ret_out epilogue hoist
# baseline (speedup 1.0000x reference)
; __device__ __forceinline__ void phase_rwkv_fused(const Frame& F, const Args& a, int l) {
;     ...
;         const int slot = item % 3;
;         if (item >= 3) { unsigned sp = 0; while ((done[slot * 2] < (unsigned)(item - 2) || done[slot * 2 + 1] < (unsigned)(item - 2)) && ++sp < (1u << 22)) __builtin_amdgcn_s_sleep(1); }
;         asm volatile("" ::: "memory");
;         LAS unsigned char* rp = ring + slot * RW_PBB;
; #pragma unroll
;         for (int ks = 0; ks < 4; ++ks) { const v2u p0 = *(const LAS v2u*)(AR + li * LDA + 16 * ks + 4 * hh), p1 = *(const LAS v2u*)(AR + li * LDA + 16 * ks + 8 + 4 * hh);
;             v4u w; w.x = p0.x; w.y = p0.y; w.z = p1.x; w.w = p1.y; *(LAS v4u*)(rp + ks * 1024 + 16 * L) = w; }
;         { const v4u w4 = *(const LAS v4u*)(M2 + li * M2D + 8 * hh); *(LAS v4u*)(rp + 4096 + 16 * L) = w4; }
;         { v4u w = {0u, 0u, 0u, 0u};
;           if (li >= 16) { const int t = li - 16; const f32x4 c0 = *(const LAS f32x4*)(GL + (16 + t) * GLD + 4 * hh), c1 = *(const LAS f32x4*)(GL + (16 + t) * GLD + 8 + 4 * hh); const int s0 = 4 * hh, s1 = 8 + 4 * hh;
;               w.x = pk2(s0 <= t ? c0.x : 0.f, s0 + 1 <= t ? c0.y : 0.f); w.y = pk2(s0 + 2 <= t ? c0.z : 0.f, s0 + 3 <= t ? c0.w : 0.f);
;               w.z = pk2(s1 <= t ? c1.x : 0.f, s1 + 1 <= t ? c1.y : 0.f); w.w = pk2(s1 + 2 <= t ? c1.z : 0.f, s1 + 3 <= t ? c1.w : 0.f); }
;           *(LAS v4u*)(rp + 9216 + 16 * L) = w; }
; #pragma unroll
;         for (int kt = 0; kt < 2; ++kt) { v4u w, w2;
; #pragma unroll
;             for (int q = 0; q < 4; ++q) { w[q] = lds_u16(BK + (16 + 8 * hh + 2 * q) * LDA + 32 * kt + li) | (lds_u16(BK + (16 + 8 * hh + 2 * q + 1) * LDA + 32 * kt + li) << 16);
;                 const int j0 = 2 * q, j1 = 2 * q + 1, s0 = 8 * (j0 >> 2) + 4 * hh + (j0 & 3), s1 = 8 * (j1 >> 2) + 4 * hh + (j1 & 3);
;                 w2[q] = lds_u16(BK + s0 * LDA + 32 * kt + li) | (lds_u16(BK + s1 * LDA + 32 * kt + li) << 16); }
;             *(LAS v4u*)(rp + 7168 + kt * 1024 + 16 * L) = w; *(LAS v4u*)(rp + 5120 + kt * 1024 + 16 * L) = w2; }
;         LDS_WAIT(); asm volatile("" ::: "memory");
;         *(LAS v4u*)(rp + 10240 + 16 * L) = frv[0]; *(LAS v4u*)(rp + 11264 + 16 * L) = frv[1];
;         *(LAS float*)(rp + 12288 + 4 * L) = gamC;
;         LDS_WAIT(); asm volatile("" ::: "memory");
;         if (L == 0) ready[slot] = (unsigned)(item + 1);
.LBB0_693:
	ds_read2_b64 v[116:119], v192 offset1:2
	ds_read2_b64 v[120:123], v192 offset0:4 offset1:6
	ds_read2_b64 v[124:127], v192 offset0:8 offset1:10
	ds_read2_b64 v[132:135], v192 offset0:12 offset1:14
	ds_read_b128 v[136:139], v160
	s_mul_i32 s16, s92, 0x3200
	s_add_i32 s16, s16, 0
	s_add_i32 s16, s16, 0x16800
	v_add_u32_e32 v108, s16, v159
	v_mov_b32_e32 v8, 0
	v_mov_b32_e32 v9, 0
	v_mov_b32_e32 v10, 0
	v_mov_b32_e32 v11, 0
	s_waitcnt lgkmcnt(0)
	ds_write_b128 v108, v[116:119]
	ds_write_b128 v108, v[120:123] offset:1024
	ds_write_b128 v108, v[124:127] offset:2048
	ds_write_b128 v108, v[132:135] offset:3072
	ds_write_b128 v108, v[136:139] offset:4096
	s_mov_b64 vcc, exec
	v_readlane_b32 s24, v255, 13
	v_readlane_b32 s25, v255, 14
	s_and_b64 s[24:25], vcc, s[24:25]
	s_mov_b64 exec, s[24:25]
	s_cbranch_execz .LBB0_695
	ds_read_b128 v[0:3], v161
	ds_read_b128 v[4:7], v161 offset:32
	v_readlane_b32 s24, v255, 15
	v_readlane_b32 s25, v255, 16
	s_waitcnt lgkmcnt(1)
	s_nop 0
	v_cndmask_b32_e64 v0, v0, 0, s[24:25]
	v_readlane_b32 s24, v255, 17
	v_readlane_b32 s25, v255, 18
	s_nop 1
	v_cndmask_b32_e64 v1, 0, v1, s[24:25]
	v_readlane_b32 s24, v255, 19
	v_readlane_b32 s25, v255, 20
	v_cvt_pk_bf16_f32 v8, v0, v1
	s_nop 0
	v_cndmask_b32_e64 v2, v2, 0, s[24:25]
	v_readlane_b32 s24, v255, 21
	v_readlane_b32 s25, v255, 22
	s_nop 1
	v_cndmask_b32_e64 v3, v3, 0, s[24:25]
	v_readlane_b32 s24, v255, 23
	v_readlane_b32 s25, v255, 24
	v_cvt_pk_bf16_f32 v9, v2, v3
	s_waitcnt lgkmcnt(0)
	v_cndmask_b32_e64 v0, v4, 0, s[24:25]
	v_readlane_b32 s24, v255, 25
	v_readlane_b32 s25, v255, 26
	s_nop 1
	v_cndmask_b32_e64 v1, v5, 0, s[24:25]
	v_readlane_b32 s24, v255, 27
	v_readlane_b32 s25, v255, 28
	v_cvt_pk_bf16_f32 v10, v0, v1
	s_nop 0
	v_cndmask_b32_e64 v0, v6, 0, s[24:25]
	v_readlane_b32 s24, v255, 29
	v_readlane_b32 s25, v255, 30
	s_nop 1
	v_cndmask_b32_e64 v1, v7, 0, s[24:25]
	v_cvt_pk_bf16_f32 v11, v0, v1
.LBB0_695:
	s_or_b64 exec, exec, vcc
	ds_write_b128 v108, v[8:11] offset:9216
	v_add_u32_e32 v109, v162, v173
	v_add_u32_e32 v114, v162, v174
	ds_read_u16 v219, v193 offset:2304
	ds_read_u16 v220, v193 offset:2448
	ds_read_u16 v221, v109
	ds_read_u16 v222, v109 offset:144
	ds_read_u16 v223, v193 offset:2592
	ds_read_u16 v224, v193 offset:2736
	ds_read_u16 v225, v114
	ds_read_u16 v226, v114 offset:144
	ds_read_u16 v227, v193 offset:2880
	ds_read_u16 v228, v193 offset:3024
	ds_read_u16 v229, v114 offset:864
	ds_read_u16 v230, v114 offset:1008
	ds_read_u16 v231, v193 offset:3168
	ds_read_u16 v232, v193 offset:3312
	ds_read_u16 v233, v114 offset:1152
	ds_read_u16 v234, v114 offset:1296
	ds_read_u16 v235, v193 offset:2368
	ds_read_u16 v236, v193 offset:2512
	ds_read_u16 v237, v109 offset:64
	ds_read_u16 v238, v109 offset:208
	ds_read_u16 v239, v193 offset:2656
	ds_read_u16 v240, v193 offset:2800
	ds_read_u16 v241, v114 offset:64
	ds_read_u16 v242, v114 offset:208
	ds_read_u16 v243, v193 offset:2944
	ds_read_u16 v244, v193 offset:3088
	ds_read_u16 v245, v114 offset:928
	ds_read_u16 v246, v114 offset:1072
	ds_read_u16 v247, v193 offset:3232
	ds_read_u16 v248, v193 offset:3376
	ds_read_u16 v249, v114 offset:1216
	ds_read_u16 v250, v114 offset:1360
	v_lshlrev_b32_e32 v0, 16, v203
	v_lshlrev_b32_e32 v1, 16, v211
	v_lshlrev_b32_e32 v2, 16, v216
	v_lshlrev_b32_e32 v3, 16, v217
	v_or_b32_sdwa v0, v0, v199 dst_sel:DWORD dst_unused:UNUSED_PAD src0_sel:DWORD src1_sel:WORD_0
	v_or_b32_sdwa v1, v1, v200 dst_sel:DWORD dst_unused:UNUSED_PAD src0_sel:DWORD src1_sel:WORD_0
	v_or_b32_sdwa v2, v2, v214 dst_sel:DWORD dst_unused:UNUSED_PAD src0_sel:DWORD src1_sel:WORD_0
	v_or_b32_sdwa v3, v3, v215 dst_sel:DWORD dst_unused:UNUSED_PAD src0_sel:DWORD src1_sel:WORD_0
	v_lshlrev_b32_e32 v4, 16, v198
	v_lshlrev_b32_e32 v5, 16, v196
	v_lshlrev_b32_e32 v6, 16, v213
	v_lshlrev_b32_e32 v7, 16, v202
	v_or_b32_sdwa v4, v4, v197 dst_sel:DWORD dst_unused:UNUSED_PAD src0_sel:DWORD src1_sel:WORD_0
	v_or_b32_sdwa v5, v5, v195 dst_sel:DWORD dst_unused:UNUSED_PAD src0_sel:DWORD src1_sel:WORD_0
	v_or_b32_sdwa v6, v6, v212 dst_sel:DWORD dst_unused:UNUSED_PAD src0_sel:DWORD src1_sel:WORD_0
	v_or_b32_sdwa v7, v7, v201 dst_sel:DWORD dst_unused:UNUSED_PAD src0_sel:DWORD src1_sel:WORD_0
	s_waitcnt lgkmcnt(0)
	v_lshl_or_b32 v8, v220, 16, v219
	v_lshl_or_b32 v110, v222, 16, v221
	v_lshl_or_b32 v9, v224, 16, v223
	v_lshl_or_b32 v111, v226, 16, v225
	v_lshl_or_b32 v10, v228, 16, v227
	v_lshl_or_b32 v112, v230, 16, v229
	v_lshl_or_b32 v11, v232, 16, v231
	v_lshl_or_b32 v113, v234, 16, v233
	ds_write_b128 v108, v[8:11] offset:7168
	ds_write_b128 v108, v[110:113] offset:5120
	v_lshl_or_b32 v116, v236, 16, v235
	v_lshl_or_b32 v120, v238, 16, v237
	v_lshl_or_b32 v117, v240, 16, v239
	v_lshl_or_b32 v121, v242, 16, v241
	v_lshl_or_b32 v118, v244, 16, v243
	v_lshl_or_b32 v122, v246, 16, v245
	v_lshl_or_b32 v119, v248, 16, v247
	v_lshl_or_b32 v123, v250, 16, v249
	ds_write_b128 v108, v[116:119] offset:8192
	ds_write_b128 v108, v[120:123] offset:6144
	s_waitcnt lgkmcnt(0)
	ds_write_b128 v108, v[0:3] offset:10240
	ds_write_b128 v108, v[4:7] offset:11264
	v_add_u32_e32 v0, s16, v150
	ds_write_b32 v0, v194 offset:12288
	s_waitcnt lgkmcnt(0)
	s_and_saveexec_b64 s[16:17], s[34:35]
	s_cbranch_execz .LBB0_636
	s_lshl_b32 s24, s92, 2
	s_add_i32 s24, s24, 0
	s_add_i32 s23, s82, 1
	s_add_i32 s24, s24, 0x1fe00
	v_mov_b32_e32 v0, s24
	v_mov_b32_e32 v1, s23
	ds_write_b32 v0, v1
	s_branch .LBB0_636
